# sample-row routine: sample-tile counter read early (start of the prompt epilogue), poll skipped when it already shows all partials posted
# speedup vs baseline: 1.0052x; 1.0044x over previous
.LBB0_308:
	v_readlane_b32 s30, v253, 41
	v_readlane_b32 s31, v253, 29
	s_lshl_b32 s38, s30, 1
	s_cmp_eq_u32 s31, 8
	s_cselect_b32 s31, 1, 0
	s_add_i32 s38, s38, s31
	v_readlane_b32 s36, v253, 42
	v_readlane_b32 s37, v253, 43
	s_lshr_b32 s25, s84, 6
	s_lshl_b32 s30, s38, 2
	s_add_i32 s25, s25, s30
	s_lshl_b32 s25, s25, 2
	s_add_i32 s25, s25, 0x8800
	s_add_u32 s36, s36, s25
	s_addc_u32 s37, s37, 0
	global_load_dword v219, v1, s[36:37] sc1
	s_ashr_i32 s25, s76, 5
	s_mul_i32 s25, s25, 0x18000
	s_add_u32 s36, s18, s25
	s_addc_u32 s37, s19, 0
	v_lshlrev_b64 v[226:227], 2, v[194:195]
	v_ashrrev_i32_e32 v193, 31, v192
	v_lshlrev_b64 v[228:229], 12, v[192:193]
	v_lshl_add_u64 v[244:245], s[36:37], 0, v[226:227]
	global_load_dwordx4 v[198:201], v[244:245], off offset:0
	global_load_dwordx4 v[202:205], v[244:245], off offset:64
	global_load_dwordx4 v[210:213], v[244:245], off offset:512
	global_load_dwordx4 v[214:217], v[244:245], off offset:576
	v_lshl_add_u64 v[242:243], s[12:13], 0, v[226:227]
	v_lshl_add_u64 v[242:243], v[242:243], 0, v[228:229]
	s_mov_b32 s31, 0
	s_mov_b32 s30, 0x0
	v_lshl_add_u64 v[246:247], v[242:243], 0, s[30:31]
	global_load_dwordx4 v[134:137], v[246:247], off offset:0
	global_load_dwordx4 v[138:141], v[246:247], off offset:64
	global_load_dwordx4 v[142:145], v[246:247], off offset:512
	global_load_dwordx4 v[146:149], v[246:247], off offset:576
	s_mov_b32 s30, 0x10000
	v_lshl_add_u64 v[246:247], v[242:243], 0, s[30:31]
	global_load_dwordx4 v[150:153], v[246:247], off offset:0
	global_load_dwordx4 v[154:157], v[246:247], off offset:64
	global_load_dwordx4 v[158:161], v[246:247], off offset:512
	global_load_dwordx4 v[162:165], v[246:247], off offset:576
	s_mov_b32 s30, 0x20000
	v_lshl_add_u64 v[246:247], v[242:243], 0, s[30:31]
	global_load_dwordx4 v[166:169], v[246:247], off offset:0
	global_load_dwordx4 v[170:173], v[246:247], off offset:64
	global_load_dwordx4 v[174:177], v[246:247], off offset:512
	global_load_dwordx4 v[178:181], v[246:247], off offset:576
	s_mov_b32 s30, 0x30000
	v_lshl_add_u64 v[246:247], v[242:243], 0, s[30:31]
	global_load_dwordx4 v[182:185], v[246:247], off offset:0
	global_load_dwordx4 v[186:189], v[246:247], off offset:64
	global_load_dwordx4 v[190:193], v[246:247], off offset:512
	global_load_dwordx4 v[194:197], v[246:247], off offset:576
	ds_bpermute_b32 v6, v222, v6
	ds_bpermute_b32 v7, v222, v7
	ds_bpermute_b32 v8, v222, v8
	ds_bpermute_b32 v9, v222, v9
	ds_bpermute_b32 v10, v222, v10
	ds_bpermute_b32 v11, v222, v11
	ds_bpermute_b32 v12, v222, v12
	ds_bpermute_b32 v13, v222, v13
	ds_bpermute_b32 v14, v222, v14
	ds_bpermute_b32 v15, v222, v15
	ds_bpermute_b32 v16, v222, v16
	ds_bpermute_b32 v17, v222, v17
	ds_bpermute_b32 v18, v222, v18
	ds_bpermute_b32 v19, v222, v19
	ds_bpermute_b32 v20, v222, v20
	ds_bpermute_b32 v21, v222, v21
	s_waitcnt lgkmcnt(8)
	ds_bpermute_b32 v22, v222, v22
	ds_bpermute_b32 v23, v222, v23
	ds_bpermute_b32 v24, v222, v24
	ds_bpermute_b32 v25, v222, v25
	ds_bpermute_b32 v26, v222, v26
	ds_bpermute_b32 v27, v222, v27
	ds_bpermute_b32 v28, v222, v28
	ds_bpermute_b32 v29, v222, v29
	s_waitcnt lgkmcnt(8)
	ds_bpermute_b32 v30, v222, v30
	ds_bpermute_b32 v31, v222, v31
	ds_bpermute_b32 v32, v222, v32
	ds_bpermute_b32 v33, v222, v33
	ds_bpermute_b32 v34, v222, v34
	ds_bpermute_b32 v35, v222, v35
	ds_bpermute_b32 v36, v222, v36
	ds_bpermute_b32 v37, v222, v37
	s_waitcnt lgkmcnt(8)
	ds_bpermute_b32 v38, v222, v38
	ds_bpermute_b32 v39, v222, v39
	ds_bpermute_b32 v40, v222, v40
	ds_bpermute_b32 v41, v222, v41
	ds_bpermute_b32 v42, v222, v42
	ds_bpermute_b32 v43, v222, v43
	ds_bpermute_b32 v44, v222, v44
	ds_bpermute_b32 v45, v222, v45
	s_waitcnt lgkmcnt(8)
	ds_bpermute_b32 v46, v222, v46
	ds_bpermute_b32 v47, v222, v47
	ds_bpermute_b32 v48, v222, v48
	ds_bpermute_b32 v49, v222, v49
	ds_bpermute_b32 v50, v222, v50
	ds_bpermute_b32 v51, v222, v51
	ds_bpermute_b32 v52, v222, v52
	ds_bpermute_b32 v53, v222, v53
	s_waitcnt lgkmcnt(8)
	ds_bpermute_b32 v54, v222, v54
	ds_bpermute_b32 v55, v222, v55
	ds_bpermute_b32 v56, v222, v56
	ds_bpermute_b32 v57, v222, v57
	ds_bpermute_b32 v58, v222, v58
	ds_bpermute_b32 v59, v222, v59
	ds_bpermute_b32 v60, v222, v60
	ds_bpermute_b32 v61, v222, v61
	s_waitcnt lgkmcnt(8)
	ds_bpermute_b32 v62, v222, v62
	ds_bpermute_b32 v63, v222, v63
	ds_bpermute_b32 v64, v222, v64
	ds_bpermute_b32 v65, v222, v65
	ds_bpermute_b32 v66, v222, v66
	ds_bpermute_b32 v67, v222, v67
	ds_bpermute_b32 v68, v222, v68
	ds_bpermute_b32 v69, v222, v69
	s_waitcnt lgkmcnt(8)
	ds_bpermute_b32 v70, v222, v70
	ds_bpermute_b32 v71, v222, v71
	ds_bpermute_b32 v72, v222, v72
	ds_bpermute_b32 v73, v222, v73
	ds_bpermute_b32 v74, v222, v74
	ds_bpermute_b32 v75, v222, v75
	ds_bpermute_b32 v76, v222, v76
	ds_bpermute_b32 v77, v222, v77
	s_waitcnt lgkmcnt(8)
	ds_bpermute_b32 v78, v222, v78
	ds_bpermute_b32 v79, v222, v79
	ds_bpermute_b32 v80, v222, v80
	ds_bpermute_b32 v81, v222, v81
	ds_bpermute_b32 v82, v222, v82
	ds_bpermute_b32 v83, v222, v83
	ds_bpermute_b32 v84, v222, v84
	ds_bpermute_b32 v85, v222, v85
	s_waitcnt lgkmcnt(8)
	ds_bpermute_b32 v86, v222, v86
	ds_bpermute_b32 v87, v222, v87
	ds_bpermute_b32 v88, v222, v88
	ds_bpermute_b32 v89, v222, v89
	ds_bpermute_b32 v90, v222, v90
	ds_bpermute_b32 v91, v222, v91
	ds_bpermute_b32 v92, v222, v92
	ds_bpermute_b32 v93, v222, v93
	s_waitcnt lgkmcnt(8)
	ds_bpermute_b32 v94, v222, v94
	ds_bpermute_b32 v95, v222, v95
	ds_bpermute_b32 v96, v222, v96
	ds_bpermute_b32 v97, v222, v97
	ds_bpermute_b32 v98, v222, v98
	ds_bpermute_b32 v99, v222, v99
	ds_bpermute_b32 v100, v222, v100
	ds_bpermute_b32 v101, v222, v101
	s_waitcnt lgkmcnt(8)
	ds_bpermute_b32 v102, v222, v102
	ds_bpermute_b32 v103, v222, v103
	ds_bpermute_b32 v104, v222, v104
	ds_bpermute_b32 v105, v222, v105
	ds_bpermute_b32 v106, v222, v106
	ds_bpermute_b32 v107, v222, v107
	ds_bpermute_b32 v108, v222, v108
	ds_bpermute_b32 v109, v222, v109
	s_waitcnt lgkmcnt(8)
	ds_bpermute_b32 v110, v222, v110
	ds_bpermute_b32 v111, v222, v111
	ds_bpermute_b32 v112, v222, v112
	ds_bpermute_b32 v113, v222, v113
	ds_bpermute_b32 v114, v222, v114
	ds_bpermute_b32 v115, v222, v115
	ds_bpermute_b32 v116, v222, v116
	ds_bpermute_b32 v117, v222, v117
	s_waitcnt lgkmcnt(8)
	ds_bpermute_b32 v118, v222, v118
	ds_bpermute_b32 v119, v222, v119
	ds_bpermute_b32 v120, v222, v120
	ds_bpermute_b32 v121, v222, v121
	ds_bpermute_b32 v122, v222, v122
	ds_bpermute_b32 v123, v222, v123
	ds_bpermute_b32 v124, v222, v124
	ds_bpermute_b32 v125, v222, v125
	s_waitcnt lgkmcnt(8)
	ds_bpermute_b32 v126, v222, v126
	ds_bpermute_b32 v127, v222, v127
	ds_bpermute_b32 v128, v222, v128
	ds_bpermute_b32 v129, v222, v129
	ds_bpermute_b32 v130, v222, v130
	ds_bpermute_b32 v131, v222, v131
	ds_bpermute_b32 v132, v222, v132
	ds_bpermute_b32 v133, v222, v133
	s_waitcnt lgkmcnt(0)
	s_waitcnt vmcnt(0)
	v_pk_fma_f32 v[130:131], v[130:131], v[198:199], v[134:135]
	v_pk_fma_f32 v[132:133], v[132:133], v[200:201], v[136:137]
	v_pk_fma_f32 v[126:127], v[126:127], v[202:203], v[138:139]
	v_pk_fma_f32 v[128:129], v[128:129], v[204:205], v[140:141]
	v_pk_fma_f32 v[122:123], v[122:123], v[210:211], v[142:143]
	v_pk_fma_f32 v[124:125], v[124:125], v[212:213], v[144:145]
	v_pk_fma_f32 v[118:119], v[118:119], v[214:215], v[146:147]
	v_pk_fma_f32 v[120:121], v[120:121], v[216:217], v[148:149]
	v_pk_fma_f32 v[114:115], v[114:115], v[198:199], v[150:151]
	v_pk_fma_f32 v[116:117], v[116:117], v[200:201], v[152:153]
	v_pk_fma_f32 v[110:111], v[110:111], v[202:203], v[154:155]
	v_pk_fma_f32 v[112:113], v[112:113], v[204:205], v[156:157]
	v_pk_fma_f32 v[106:107], v[106:107], v[210:211], v[158:159]
	v_pk_fma_f32 v[108:109], v[108:109], v[212:213], v[160:161]
	v_pk_fma_f32 v[102:103], v[102:103], v[214:215], v[162:163]
	v_pk_fma_f32 v[104:105], v[104:105], v[216:217], v[164:165]
	v_pk_fma_f32 v[98:99], v[98:99], v[198:199], v[166:167]
	v_pk_fma_f32 v[100:101], v[100:101], v[200:201], v[168:169]
	v_pk_fma_f32 v[94:95], v[94:95], v[202:203], v[170:171]
	v_pk_fma_f32 v[96:97], v[96:97], v[204:205], v[172:173]
	v_pk_fma_f32 v[90:91], v[90:91], v[210:211], v[174:175]
	v_pk_fma_f32 v[92:93], v[92:93], v[212:213], v[176:177]
	v_pk_fma_f32 v[86:87], v[86:87], v[214:215], v[178:179]
	v_pk_fma_f32 v[88:89], v[88:89], v[216:217], v[180:181]
	v_pk_fma_f32 v[82:83], v[82:83], v[198:199], v[182:183]
	v_pk_fma_f32 v[84:85], v[84:85], v[200:201], v[184:185]
	v_pk_fma_f32 v[78:79], v[78:79], v[202:203], v[186:187]
	v_pk_fma_f32 v[80:81], v[80:81], v[204:205], v[188:189]
	v_pk_fma_f32 v[74:75], v[74:75], v[210:211], v[190:191]
	v_pk_fma_f32 v[76:77], v[76:77], v[212:213], v[192:193]
	v_pk_fma_f32 v[70:71], v[70:71], v[214:215], v[194:195]
	v_pk_fma_f32 v[72:73], v[72:73], v[216:217], v[196:197]
	s_mov_b32 s30, 0x80000
	v_lshl_add_u64 v[246:247], v[242:243], 0, s[30:31]
	global_load_dwordx4 v[134:137], v[246:247], off offset:0
	global_load_dwordx4 v[138:141], v[246:247], off offset:64
	global_load_dwordx4 v[142:145], v[246:247], off offset:512
	global_load_dwordx4 v[146:149], v[246:247], off offset:576
	s_mov_b32 s30, 0x90000
	v_lshl_add_u64 v[246:247], v[242:243], 0, s[30:31]
	global_load_dwordx4 v[150:153], v[246:247], off offset:0
	global_load_dwordx4 v[154:157], v[246:247], off offset:64
	global_load_dwordx4 v[158:161], v[246:247], off offset:512
	global_load_dwordx4 v[162:165], v[246:247], off offset:576
	s_mov_b32 s30, 0xa0000
	v_lshl_add_u64 v[246:247], v[242:243], 0, s[30:31]
	global_load_dwordx4 v[166:169], v[246:247], off offset:0
	global_load_dwordx4 v[170:173], v[246:247], off offset:64
	global_load_dwordx4 v[174:177], v[246:247], off offset:512
	global_load_dwordx4 v[178:181], v[246:247], off offset:576
	s_mov_b32 s30, 0xb0000
	v_lshl_add_u64 v[246:247], v[242:243], 0, s[30:31]
	global_load_dwordx4 v[182:185], v[246:247], off offset:0
	global_load_dwordx4 v[186:189], v[246:247], off offset:64
	global_load_dwordx4 v[190:193], v[246:247], off offset:512
	global_load_dwordx4 v[194:197], v[246:247], off offset:576
	s_waitcnt vmcnt(0)
	v_pk_fma_f32 v[66:67], v[66:67], v[198:199], v[134:135]
	v_pk_fma_f32 v[68:69], v[68:69], v[200:201], v[136:137]
	v_pk_fma_f32 v[62:63], v[62:63], v[202:203], v[138:139]
	v_pk_fma_f32 v[64:65], v[64:65], v[204:205], v[140:141]
	v_pk_fma_f32 v[58:59], v[58:59], v[210:211], v[142:143]
	v_pk_fma_f32 v[60:61], v[60:61], v[212:213], v[144:145]
	v_pk_fma_f32 v[54:55], v[54:55], v[214:215], v[146:147]
	v_pk_fma_f32 v[56:57], v[56:57], v[216:217], v[148:149]
	v_pk_fma_f32 v[50:51], v[50:51], v[198:199], v[150:151]
	v_pk_fma_f32 v[52:53], v[52:53], v[200:201], v[152:153]
	v_pk_fma_f32 v[46:47], v[46:47], v[202:203], v[154:155]
	v_pk_fma_f32 v[48:49], v[48:49], v[204:205], v[156:157]
	v_pk_fma_f32 v[42:43], v[42:43], v[210:211], v[158:159]
	v_pk_fma_f32 v[44:45], v[44:45], v[212:213], v[160:161]
	v_pk_fma_f32 v[38:39], v[38:39], v[214:215], v[162:163]
	v_pk_fma_f32 v[40:41], v[40:41], v[216:217], v[164:165]
	v_pk_fma_f32 v[34:35], v[34:35], v[198:199], v[166:167]
	v_pk_fma_f32 v[36:37], v[36:37], v[200:201], v[168:169]
	v_pk_fma_f32 v[30:31], v[30:31], v[202:203], v[170:171]
	v_pk_fma_f32 v[32:33], v[32:33], v[204:205], v[172:173]
	v_pk_fma_f32 v[26:27], v[26:27], v[210:211], v[174:175]
	v_pk_fma_f32 v[28:29], v[28:29], v[212:213], v[176:177]
	v_pk_fma_f32 v[22:23], v[22:23], v[214:215], v[178:179]
	v_pk_fma_f32 v[24:25], v[24:25], v[216:217], v[180:181]
	v_pk_fma_f32 v[18:19], v[18:19], v[198:199], v[182:183]
	v_pk_fma_f32 v[20:21], v[20:21], v[200:201], v[184:185]
	v_pk_fma_f32 v[14:15], v[14:15], v[202:203], v[186:187]
	v_pk_fma_f32 v[16:17], v[16:17], v[204:205], v[188:189]
	v_pk_fma_f32 v[10:11], v[10:11], v[210:211], v[190:191]
	v_pk_fma_f32 v[12:13], v[12:13], v[212:213], v[192:193]
	v_pk_fma_f32 v[6:7], v[6:7], v[214:215], v[194:195]
	v_pk_fma_f32 v[8:9], v[8:9], v[216:217], v[196:197]
	s_cmp_eq_u32 s38, 7
	s_cbranch_scc1 .Lrn_final_p
	s_and_b32 s25, s38, 1
	s_lshr_b32 s30, s38, 1
	s_cmp_eq_u32 s25, 0
	s_cbranch_scc1 .Lrn_ffn_p
	s_add_i32 s30, s30, 1
	s_movk_i32 s25, 0x48
	s_mul_i32 s31, s30, 0x6000
	s_branch .Lrn_p_done

.LBB0_312:
	s_waitcnt vmcnt(0)
	v_readlane_b32 s70, v253, 32
	v_readlane_b32 s71, v253, 33
	v_readlane_b32 s72, v253, 34
	v_readlane_b32 s74, v253, 36
	s_barrier
	s_movk_i32 s67, 0x82
	s_mov_b32 s68, 0xc0135761
	v_readlane_b32 s69, v253, 53
	v_readlane_b32 s73, v253, 35
	v_readlane_b32 s75, v253, 37
	v_readlane_b32 s71, v253, 38
	v_readlane_b32 s25, v253, 41
	v_readfirstlane_b32 s2, v230
	s_lshr_b32 s2, s2, 6
	s_cmp_gt_u32 s2, 3
	s_cbranch_scc1 .Lsn_done
	s_lshl_b32 s3, s84, 2
	s_add_i32 s3, s3, s2
	v_readlane_b32 s4, v253, 29
	s_cmp_eq_u32 s4, 8
	s_cselect_b32 s6, 1, 0
	s_cselect_b32 s7, 44, 32
	s_lshl_b32 s5, s25, 1
	s_add_i32 s5, s5, s6
	v_readlane_b32 s8, v253, 42
	v_readlane_b32 s9, v253, 43
	s_lshr_b32 s10, s3, 8
	s_lshl_b32 s11, s5, 2
	s_add_i32 s11, s11, s10
	s_lshl_b32 s11, s11, 2
	s_add_i32 s11, s11, 0x8800
	s_add_u32 s12, s8, s11
	s_addc_u32 s13, s9, 0
	s_mov_b32 s14, 0
	v_readfirstlane_b32 s15, v219
	s_cmp_ge_u32 s15, s7
	s_cbranch_scc1 .Lsn_ready
